# RG-LRU cross-chunk carry loops in the mix phase (forward and reverse): all 8 LDS reads of an iteration issued up front with counted lgkmcnt waits instead of read-wait-compute-write per step
# speedup vs baseline: 1.0041x; 1.0041x over previous
.LBB0_799:
	v_add_u32_e32 v70, s28, v172
	ds_read2st64_b32 v[64:65], v70 offset1:2
	ds_read2st64_b32 v[66:67], v70 offset0:64 offset1:66
	ds_read2st64_b32 v[218:219], v70 offset0:4 offset1:6
	ds_read2st64_b32 v[68:69], v70 offset0:68 offset1:70
	ds_read2st64_b32 v[220:221], v70 offset0:8 offset1:10
	ds_read2st64_b32 v[222:223], v70 offset0:72 offset1:74
	ds_read2st64_b32 v[224:225], v70 offset0:12 offset1:14
	ds_read2st64_b32 v[226:227], v70 offset0:76 offset1:78
	s_addk_i32 s28, 0x1000
	s_cmpk_lg_i32 s28, 0x4000
	s_waitcnt lgkmcnt(6)
	v_fma_f32 v64, v91, v64, v66
	v_fmac_f32_e32 v67, v64, v65
	ds_write2st64_b32 v70, v64, v67 offset0:64 offset1:66
	s_waitcnt lgkmcnt(5)
	v_fma_f32 v218, v67, v218, v68
	v_fmac_f32_e32 v69, v218, v219
	ds_write2st64_b32 v70, v218, v69 offset0:68 offset1:70
	s_waitcnt lgkmcnt(4)
	v_fma_f32 v220, v69, v220, v222
	v_fmac_f32_e32 v223, v220, v221
	ds_write2st64_b32 v70, v220, v223 offset0:72 offset1:74
	s_waitcnt lgkmcnt(3)
	v_fma_f32 v224, v223, v224, v226
	v_fmac_f32_e32 v227, v224, v225
	ds_write2st64_b32 v70, v224, v227 offset0:76 offset1:78
	v_mov_b32_e32 v91, v227
	s_cbranch_scc1 .LBB0_799

.LBB0_888:
	v_add_u32_e32 v70, s8, v173
	ds_read2st64_b32 v[64:65], v70 offset0:12 offset1:14
	ds_read2st64_b32 v[66:67], v70 offset0:76 offset1:78
	ds_read2st64_b32 v[218:219], v70 offset0:8 offset1:10
	ds_read2st64_b32 v[68:69], v70 offset0:72 offset1:74
	ds_read2st64_b32 v[220:221], v70 offset0:4 offset1:6
	ds_read2st64_b32 v[222:223], v70 offset0:68 offset1:70
	ds_read2st64_b32 v[224:225], v70 offset1:2
	ds_read2st64_b32 v[226:227], v70 offset0:64 offset1:66
	s_addk_i32 s8, 0xf000
	s_cmpk_lg_i32 s8, 0x1200
	s_waitcnt lgkmcnt(6)
	v_fma_f32 v65, v90, v65, v67
	v_fmac_f32_e32 v66, v65, v64
	ds_write2st64_b32 v70, v66, v65 offset0:76 offset1:78
	s_waitcnt lgkmcnt(5)
	v_fma_f32 v219, v66, v219, v69
	v_fmac_f32_e32 v68, v219, v218
	ds_write2st64_b32 v70, v68, v219 offset0:72 offset1:74
	s_waitcnt lgkmcnt(4)
	v_fma_f32 v221, v68, v221, v223
	v_fmac_f32_e32 v222, v221, v220
	ds_write2st64_b32 v70, v222, v221 offset0:68 offset1:70
	s_waitcnt lgkmcnt(3)
	v_fma_f32 v225, v222, v225, v227
	v_fmac_f32_e32 v226, v225, v224
	ds_write2st64_b32 v70, v226, v225 offset0:64 offset1:66
	v_mov_b32_e32 v90, v226
	s_cbranch_scc1 .LBB0_888
	s_branch .LBB0_847
